# sample-group attention item: query-fragment loads issued at the top of the item and the V-tile loads issued right after the K-tile loads (renamed registers), so the three HBM round trips of an item ov
# speedup vs baseline: 1.0008x; 1.0008x over previous
.LBB0_1221:
	v_mov_b32_e32 v162, v0
	s_add_i32 s0, s14, 0xfffffd80
	v_ashrrev_i32_e32 v66, 5, v162
	v_lshlrev_b32_e32 v2, 2, v162
	v_ashrrev_i32_e32 v67, 31, v66
	v_and_b32_e32 v98, 0x7c, v2
	v_lshlrev_b64 v[2:3], 11, v[66:67]
	v_add_u32_e32 v67, 0x200, v162
	v_ashrrev_i32_e32 v68, 5, v67
	v_ashrrev_i32_e32 v69, 31, v68
	v_lshlrev_b64 v[4:5], 11, v[68:69]
	v_add_u32_e32 v69, 0x400, v162
	v_ashrrev_i32_e32 v70, 5, v69
	v_ashrrev_i32_e32 v71, 31, v70
	v_lshlrev_b64 v[10:11], 11, v[70:71]
	v_add_u32_e32 v71, 0x600, v162
	s_ashr_i32 s4, s0, 2
	v_ashrrev_i32_e32 v72, 5, v71
	s_lshl_b32 s0, s4, 3
	s_lshl_b32 s5, s14, 7
	v_ashrrev_i32_e32 v73, 31, v72
	s_addk_i32 s0, 0x4000
	s_and_b32 s12, s5, 0x180
	s_ashr_i32 s5, s4, 31
	v_readlane_b32 s16, v245, 6
	v_lshlrev_b64 v[12:13], 11, v[72:73]
	v_add_u32_e32 v73, 0x800, v162
	s_ashr_i32 s1, s0, 31
	s_lshl_b64 s[4:5], s[4:5], 19
	v_readlane_b32 s24, v245, 14
	v_ashrrev_i32_e32 v74, 5, v73
	v_readlane_b32 s25, v245, 15
	s_add_u32 s6, s24, s4
	v_ashrrev_i32_e32 v75, 31, v74
	s_addc_u32 s7, s25, s5
	s_lshl_b32 s13, s12, 2
	v_lshlrev_b64 v[18:19], 11, v[74:75]
	v_add_u32_e32 v75, 0xa00, v162
	s_add_u32 s6, s6, s13
	v_ashrrev_i32_e32 v76, 5, v75
	s_addc_u32 s7, s7, 0
	v_lshlrev_b32_e32 v158, 2, v98
	v_ashrrev_i32_e32 v77, 31, v76
	v_lshl_add_u64 v[62:63], s[6:7], 0, v[158:159]
	v_lshlrev_b64 v[20:21], 11, v[76:77]
	v_add_u32_e32 v77, 0xc00, v162
	v_lshl_add_u64 v[2:3], v[62:63], 0, v[2:3]
	v_lshl_add_u64 v[6:7], v[62:63], 0, v[4:5]
	v_ashrrev_i32_e32 v78, 5, v77
	v_readfirstlane_b32 s6, v0
	s_nop 3
	s_cmp_gt_u32 s6, 63
	s_cbranch_scc1 .Lsaq_skip
	s_lshl_b64 s[6:7], s[0:1], 10
	s_add_u32 s6, s41, s6
	s_addc_u32 s7, s42, s7
	s_add_u32 s6, s6, s12
	s_addc_u32 s7, s7, 0
	s_add_u32 s6, s6, s12
	s_addc_u32 s7, s7, 0
	v_and_b32_e32 v172, 31, v162
	v_bfe_u32 v173, v162, 5, 1
	v_lshlrev_b32_e32 v170, 10, v172
	v_lshl_add_u32 v170, v173, 4, v170
	v_cmp_gt_u32_e32 vcc, 8, v172
	v_mov_b32_e32 v166, 0
	v_mov_b32_e32 v167, 0
	v_mov_b32_e32 v168, 0
	v_mov_b32_e32 v169, 0
	v_mov_b32_e32 v130, 0
	v_mov_b32_e32 v131, 0
	v_mov_b32_e32 v132, 0
	v_mov_b32_e32 v133, 0
	v_mov_b32_e32 v138, 0
	v_mov_b32_e32 v139, 0
	v_mov_b32_e32 v140, 0
	v_mov_b32_e32 v141, 0
	v_mov_b32_e32 v134, 0
	v_mov_b32_e32 v135, 0
	v_mov_b32_e32 v136, 0
	v_mov_b32_e32 v137, 0
	v_mov_b32_e32 v146, 0
	v_mov_b32_e32 v147, 0
	v_mov_b32_e32 v148, 0
	v_mov_b32_e32 v149, 0
	v_mov_b32_e32 v142, 0
	v_mov_b32_e32 v143, 0
	v_mov_b32_e32 v144, 0
	v_mov_b32_e32 v145, 0
	v_mov_b32_e32 v154, 0
	v_mov_b32_e32 v155, 0
	v_mov_b32_e32 v156, 0
	v_mov_b32_e32 v157, 0
	v_mov_b32_e32 v150, 0
	v_mov_b32_e32 v151, 0
	v_mov_b32_e32 v152, 0
	v_mov_b32_e32 v153, 0
	s_and_b64 exec, exec, vcc
	global_load_dwordx4 v[166:169], v170, s[6:7]
	global_load_dwordx4 v[130:133], v170, s[6:7] offset:32
	global_load_dwordx4 v[138:141], v170, s[6:7] offset:64
	global_load_dwordx4 v[134:137], v170, s[6:7] offset:96
	global_load_dwordx4 v[146:149], v170, s[6:7] offset:128
	global_load_dwordx4 v[142:145], v170, s[6:7] offset:160
	global_load_dwordx4 v[154:157], v170, s[6:7] offset:192
	global_load_dwordx4 v[150:153], v170, s[6:7] offset:224
	s_mov_b64 exec, -1
.Lsaq_skip:
	s_barrier
	global_load_dwordx4 v[2:5], v[2:3], off nt
	s_nop 0
	global_load_dwordx4 v[6:9], v[6:7], off nt
	v_ashrrev_i32_e32 v79, 31, v78
	v_lshl_add_u64 v[10:11], v[62:63], 0, v[10:11]
	v_lshl_add_u64 v[14:15], v[62:63], 0, v[12:13]
	v_lshlrev_b64 v[26:27], 11, v[78:79]
	v_add_u32_e32 v79, 0xe00, v162
	global_load_dwordx4 v[10:13], v[10:11], off nt
	s_nop 0
	global_load_dwordx4 v[14:17], v[14:15], off nt
	v_ashrrev_i32_e32 v80, 5, v79
	v_lshl_add_u64 v[18:19], v[62:63], 0, v[18:19]
	v_lshl_add_u64 v[22:23], v[62:63], 0, v[20:21]
	v_ashrrev_i32_e32 v81, 31, v80
	v_add_u32_e32 v34, 0x1000, v162
	v_add_u32_e32 v36, 0x1200, v162
	global_load_dwordx4 v[18:21], v[18:19], off nt
	s_nop 0
	global_load_dwordx4 v[22:25], v[22:23], off nt
	v_lshlrev_b64 v[28:29], 11, v[80:81]
	v_ashrrev_i32_e32 v82, 5, v34
	v_ashrrev_i32_e32 v84, 5, v36
	v_lshl_add_u64 v[26:27], v[62:63], 0, v[26:27]
	s_waitcnt vmcnt(30)
	v_lshl_add_u64 v[30:31], v[62:63], 0, v[28:29]
	v_ashrrev_i32_e32 v83, 31, v82
	v_ashrrev_i32_e32 v85, 31, v84
	s_waitcnt vmcnt(28)
	v_add_u32_e32 v42, 0x1400, v162
	s_waitcnt vmcnt(22)
	v_add_u32_e32 v44, 0x1600, v162
	global_load_dwordx4 v[26:29], v[26:27], off nt
	s_nop 0
	global_load_dwordx4 v[30:33], v[30:31], off nt
	v_lshlrev_b64 v[34:35], 11, v[82:83]
	v_lshlrev_b64 v[36:37], 11, v[84:85]
	v_ashrrev_i32_e32 v86, 5, v42
	v_ashrrev_i32_e32 v88, 5, v44
	s_waitcnt vmcnt(22)
	v_add_u32_e32 v50, 0x1800, v162
	v_lshl_add_u64 v[34:35], v[62:63], 0, v[34:35]
	v_lshl_add_u64 v[38:39], v[62:63], 0, v[36:37]
	v_ashrrev_i32_e32 v87, 31, v86
	v_ashrrev_i32_e32 v89, 31, v88
	v_ashrrev_i32_e32 v90, 5, v50
	v_add_u32_e32 v54, 0x1a00, v162
	global_load_dwordx4 v[34:37], v[34:35], off nt
	s_nop 0
	global_load_dwordx4 v[38:41], v[38:39], off nt
	v_lshlrev_b64 v[42:43], 11, v[86:87]
	s_waitcnt vmcnt(23)
	v_lshlrev_b64 v[44:45], 11, v[88:89]
	v_ashrrev_i32_e32 v91, 31, v90
	v_ashrrev_i32_e32 v92, 5, v54
	v_add_u32_e32 v58, 0x1c00, v162
	v_lshl_add_u64 v[42:43], v[62:63], 0, v[42:43]
	s_waitcnt vmcnt(20)
	v_lshl_add_u64 v[46:47], v[62:63], 0, v[44:45]
	v_lshlrev_b64 v[50:51], 11, v[90:91]
	v_ashrrev_i32_e32 v93, 31, v92
	v_ashrrev_i32_e32 v94, 5, v58
	v_add_u32_e32 v64, 0x1e00, v162
	global_load_dwordx4 v[42:45], v[42:43], off nt
	s_nop 0
	global_load_dwordx4 v[46:49], v[46:47], off nt
	v_lshl_add_u64 v[50:51], v[62:63], 0, v[50:51]
	v_lshlrev_b64 v[54:55], 11, v[92:93]
	v_ashrrev_i32_e32 v95, 31, v94
	v_ashrrev_i32_e32 v96, 5, v64
	global_load_dwordx4 v[50:53], v[50:51], off nt
	v_lshl_add_u64 v[54:55], v[62:63], 0, v[54:55]
	v_lshlrev_b64 v[58:59], 11, v[94:95]
	v_ashrrev_i32_e32 v97, 31, v96
	global_load_dwordx4 v[54:57], v[54:55], off nt
	v_lshl_add_u64 v[58:59], v[62:63], 0, v[58:59]
	v_lshlrev_b64 v[64:65], 11, v[96:97]
	global_load_dwordx4 v[58:61], v[58:59], off nt
	v_lshl_add_u64 v[62:63], v[62:63], 0, v[64:65]
	global_load_dwordx4 v[62:65], v[62:63], off nt
	v_lshl_add_u32 v98, v98, 1, 0
	v_readlane_b32 s26, v245, 16
	v_readlane_b32 s27, v245, 17
	s_add_u32 s4, s26, s4
	s_addc_u32 s5, s27, s5
	s_add_u32 s4, s4, s13
	s_addc_u32 s5, s5, 0
	v_ashrrev_i32_e32 v67, 4, v67
	v_and_b32_e32 v163, 31, v162
	v_readfirstlane_b32 s13, v0
	v_bfe_u32 v164, v162, 5, 1
	s_cmp_lt_u32 s13, 64
	v_lshlrev_b32_e32 v160, 4, v164
	v_readlane_b32 s17, v245, 7
	v_readlane_b32 s18, v245, 8
	v_readlane_b32 s19, v245, 9
	v_readlane_b32 s20, v245, 10
	v_ashrrev_i32_e32 v238, 4, v162
	v_and_b32_e32 v174, -2, v238
	v_or_b32_e32 v176, 1, v238
	v_ashrrev_i32_e32 v175, 31, v174
	v_ashrrev_i32_e32 v177, 31, v176
	v_lshl_add_u64 v[230:231], s[4:5], 0, v[158:159]
	v_lshlrev_b64 v[174:175], 11, v[174:175]
	v_lshlrev_b64 v[176:177], 11, v[176:177]
	v_lshl_add_u64 v[174:175], v[230:231], 0, v[174:175]
	v_lshl_add_u64 v[178:179], v[230:231], 0, v[176:177]
	global_load_dwordx4 v[174:177], v[174:175], off nt
	s_nop 0
	global_load_dwordx4 v[178:181], v[178:179], off nt
	v_and_b32_e32 v182, -2, v67
	v_or_b32_e32 v184, 1, v67
	v_ashrrev_i32_e32 v183, 31, v182
	v_ashrrev_i32_e32 v185, 31, v184
	v_lshlrev_b64 v[182:183], 11, v[182:183]
	v_lshlrev_b64 v[184:185], 11, v[184:185]
	v_lshl_add_u64 v[182:183], v[230:231], 0, v[182:183]
	v_lshl_add_u64 v[186:187], v[230:231], 0, v[184:185]
	global_load_dwordx4 v[182:185], v[182:183], off nt
	s_nop 0
	global_load_dwordx4 v[186:189], v[186:187], off nt
	v_ashrrev_i32_e32 v239, 4, v69
	v_and_b32_e32 v190, -2, v239
	v_or_b32_e32 v192, 1, v239
	v_ashrrev_i32_e32 v191, 31, v190
	v_ashrrev_i32_e32 v193, 31, v192
	v_lshlrev_b64 v[190:191], 11, v[190:191]
	v_lshlrev_b64 v[192:193], 11, v[192:193]
	v_lshl_add_u64 v[190:191], v[230:231], 0, v[190:191]
	v_lshl_add_u64 v[194:195], v[230:231], 0, v[192:193]
	global_load_dwordx4 v[190:193], v[190:191], off nt
	s_nop 0
	global_load_dwordx4 v[194:197], v[194:195], off nt
	v_ashrrev_i32_e32 v240, 4, v71
	v_and_b32_e32 v198, -2, v240
	v_or_b32_e32 v200, 1, v240
	v_ashrrev_i32_e32 v199, 31, v198
	v_ashrrev_i32_e32 v201, 31, v200
	v_lshlrev_b64 v[198:199], 11, v[198:199]
	v_lshlrev_b64 v[200:201], 11, v[200:201]
	v_lshl_add_u64 v[198:199], v[230:231], 0, v[198:199]
	v_lshl_add_u64 v[202:203], v[230:231], 0, v[200:201]
	global_load_dwordx4 v[198:201], v[198:199], off nt
	s_nop 0
	global_load_dwordx4 v[202:205], v[202:203], off nt
	v_ashrrev_i32_e32 v241, 4, v73
	v_and_b32_e32 v206, -2, v241
	v_or_b32_e32 v208, 1, v241
	v_ashrrev_i32_e32 v207, 31, v206
	v_ashrrev_i32_e32 v209, 31, v208
	v_lshlrev_b64 v[206:207], 11, v[206:207]
	v_lshlrev_b64 v[208:209], 11, v[208:209]
	v_lshl_add_u64 v[206:207], v[230:231], 0, v[206:207]
	v_lshl_add_u64 v[210:211], v[230:231], 0, v[208:209]
	global_load_dwordx4 v[206:209], v[206:207], off nt
	s_nop 0
	global_load_dwordx4 v[210:213], v[210:211], off nt
	v_ashrrev_i32_e32 v242, 4, v75
	v_and_b32_e32 v214, -2, v242
	v_or_b32_e32 v216, 1, v242
	v_ashrrev_i32_e32 v215, 31, v214
	v_ashrrev_i32_e32 v217, 31, v216
	v_lshlrev_b64 v[214:215], 11, v[214:215]
	v_lshlrev_b64 v[216:217], 11, v[216:217]
	v_lshl_add_u64 v[214:215], v[230:231], 0, v[214:215]
	v_lshl_add_u64 v[218:219], v[230:231], 0, v[216:217]
	global_load_dwordx4 v[214:217], v[214:215], off nt
	s_nop 0
	global_load_dwordx4 v[218:221], v[218:219], off nt
	v_ashrrev_i32_e32 v243, 4, v77
	v_and_b32_e32 v222, -2, v243
	v_or_b32_e32 v224, 1, v243
	v_ashrrev_i32_e32 v223, 31, v222
	v_ashrrev_i32_e32 v225, 31, v224
	v_lshlrev_b64 v[222:223], 11, v[222:223]
	v_lshlrev_b64 v[224:225], 11, v[224:225]
	v_lshl_add_u64 v[222:223], v[230:231], 0, v[222:223]
	v_lshl_add_u64 v[226:227], v[230:231], 0, v[224:225]
	global_load_dwordx4 v[222:225], v[222:223], off nt
	s_nop 0
	global_load_dwordx4 v[226:229], v[226:227], off nt
	v_ashrrev_i32_e32 v165, 4, v79
	v_and_b32_e32 v232, -2, v165
	v_or_b32_e32 v234, 1, v165
	v_ashrrev_i32_e32 v233, 31, v232
	v_ashrrev_i32_e32 v235, 31, v234
	v_lshlrev_b64 v[232:233], 11, v[232:233]
	v_lshlrev_b64 v[234:235], 11, v[234:235]
	v_lshl_add_u64 v[232:233], v[230:231], 0, v[232:233]
	v_lshl_add_u64 v[234:235], v[230:231], 0, v[234:235]
	global_load_dwordx4 v[230:233], v[232:233], off nt
	s_nop 0
	global_load_dwordx4 v[234:237], v[234:235], off nt
	s_waitcnt vmcnt(31)
	v_cvt_pk_bf16_f32 v2, v2, v3
	v_cvt_pk_bf16_f32 v3, v4, v5
	v_mad_u64_u32 v[4:5], s[6:7], v66, s3, v[98:99]
	ds_write_b64 v4, v[2:3]
	s_waitcnt vmcnt(30)
	v_cvt_pk_bf16_f32 v2, v6, v7
	v_cvt_pk_bf16_f32 v3, v8, v9
	v_mad_u64_u32 v[4:5], s[6:7], v68, s3, v[98:99]
	ds_write_b64 v4, v[2:3]
	s_waitcnt vmcnt(29)
	v_cvt_pk_bf16_f32 v2, v10, v11
	v_cvt_pk_bf16_f32 v3, v12, v13
	v_mad_u64_u32 v[4:5], s[6:7], v70, s3, v[98:99]
	ds_write_b64 v4, v[2:3]
	s_waitcnt vmcnt(28)
	v_cvt_pk_bf16_f32 v2, v14, v15
	v_cvt_pk_bf16_f32 v3, v16, v17
	v_mad_u64_u32 v[4:5], s[6:7], v72, s3, v[98:99]
	ds_write_b64 v4, v[2:3]
	s_waitcnt vmcnt(27)
	v_cvt_pk_bf16_f32 v2, v18, v19
	v_cvt_pk_bf16_f32 v3, v20, v21
	v_mad_u64_u32 v[4:5], s[6:7], v74, s3, v[98:99]
	ds_write_b64 v4, v[2:3]
	s_waitcnt vmcnt(26)
	v_cvt_pk_bf16_f32 v2, v22, v23
	v_cvt_pk_bf16_f32 v3, v24, v25
	v_mad_u64_u32 v[4:5], s[6:7], v76, s3, v[98:99]
	ds_write_b64 v4, v[2:3]
	s_waitcnt vmcnt(25)
	v_cvt_pk_bf16_f32 v2, v26, v27
	v_cvt_pk_bf16_f32 v3, v28, v29
	v_mad_u64_u32 v[4:5], s[6:7], v78, s3, v[98:99]
	ds_write_b64 v4, v[2:3]
	s_waitcnt vmcnt(24)
	v_cvt_pk_bf16_f32 v2, v30, v31
	v_cvt_pk_bf16_f32 v3, v32, v33
	v_mad_u64_u32 v[4:5], s[6:7], v80, s3, v[98:99]
	ds_write_b64 v4, v[2:3]
	s_waitcnt vmcnt(23)
	v_cvt_pk_bf16_f32 v2, v34, v35
	v_cvt_pk_bf16_f32 v3, v36, v37
	v_mad_u64_u32 v[4:5], s[6:7], v82, s3, v[98:99]
	ds_write_b64 v4, v[2:3]
	s_waitcnt vmcnt(22)
	v_cvt_pk_bf16_f32 v2, v38, v39
	v_cvt_pk_bf16_f32 v3, v40, v41
	v_mad_u64_u32 v[4:5], s[6:7], v84, s3, v[98:99]
	ds_write_b64 v4, v[2:3]
	s_waitcnt vmcnt(21)
	v_cvt_pk_bf16_f32 v2, v42, v43
	v_cvt_pk_bf16_f32 v3, v44, v45
	v_mad_u64_u32 v[4:5], s[6:7], v86, s3, v[98:99]
	ds_write_b64 v4, v[2:3]
	s_waitcnt vmcnt(20)
	v_cvt_pk_bf16_f32 v2, v46, v47
	v_cvt_pk_bf16_f32 v3, v48, v49
	v_mad_u64_u32 v[4:5], s[6:7], v88, s3, v[98:99]
	ds_write_b64 v4, v[2:3]
	s_waitcnt vmcnt(19)
	v_cvt_pk_bf16_f32 v2, v50, v51
	v_cvt_pk_bf16_f32 v3, v52, v53
	v_mad_u64_u32 v[4:5], s[6:7], v90, s3, v[98:99]
	ds_write_b64 v4, v[2:3]
	s_waitcnt vmcnt(18)
	v_cvt_pk_bf16_f32 v2, v54, v55
	v_cvt_pk_bf16_f32 v3, v56, v57
	v_mad_u64_u32 v[4:5], s[6:7], v92, s3, v[98:99]
	ds_write_b64 v4, v[2:3]
	s_waitcnt vmcnt(17)
	v_cvt_pk_bf16_f32 v2, v58, v59
	v_cvt_pk_bf16_f32 v3, v60, v61
	v_mad_u64_u32 v[4:5], s[6:7], v94, s3, v[98:99]
	ds_write_b64 v4, v[2:3]
	s_waitcnt vmcnt(16)
	v_cvt_pk_bf16_f32 v2, v62, v63
	v_cvt_pk_bf16_f32 v3, v64, v65
	v_mad_u64_u32 v[4:5], s[6:7], v96, s3, v[98:99]
	ds_write_b64 v4, v[2:3]
	v_lshlrev_b32_e32 v75, 1, v238
	v_lshlrev_b32_e32 v74, 3, v163
	v_and_b32_e32 v76, 8, v75
	v_and_b32_e32 v77, 0x7ffffff0, v238
	v_bitop3_b32 v76, v76, v74, v77 bitop3:0x36
	v_lshlrev_b32_e32 v76, 1, v76
	v_and_b32_e32 v75, 4, v75
	v_add3_u32 v75, s37, v76, v75
	v_and_b32_e32 v238, 8, v238
	s_cselect_b64 s[4:5], -1, 0
	s_waitcnt vmcnt(14)
	v_cvt_pk_bf16_f32 v174, v174, v178
	v_mul_u32_u24_e32 v178, 0x840, v163
	v_add3_u32 v238, v75, v238, v178
	v_cvt_pk_bf16_f32 v175, v175, v179
	ds_write2_b32 v238, v174, v175 offset1:132
	v_cvt_pk_bf16_f32 v174, v176, v180
	v_cvt_pk_bf16_f32 v175, v177, v181
	v_add_u32_e32 v176, 0x400, v238
	ds_write2_b32 v176, v174, v175 offset0:8 offset1:140
	v_lshlrev_b32_e32 v174, 1, v67
	v_and_b32_e32 v175, 8, v174
	v_and_b32_e32 v176, 0x7ffffff0, v67
	v_bitop3_b32 v175, v175, v74, v176 bitop3:0x36
	v_lshlrev_b32_e32 v175, 1, v175
	v_and_b32_e32 v174, 4, v174
	v_add3_u32 v174, s37, v175, v174
	v_and_b32_e32 v175, 8, v67
	s_waitcnt vmcnt(12)
	v_cvt_pk_bf16_f32 v176, v182, v186
	v_add3_u32 v174, v174, v175, v178
	v_cvt_pk_bf16_f32 v175, v183, v187
	ds_write2_b32 v174, v176, v175 offset1:132
	v_cvt_pk_bf16_f32 v175, v184, v188
	v_cvt_pk_bf16_f32 v176, v185, v189
	v_add_u32_e32 v174, 0x400, v174
	ds_write2_b32 v174, v175, v176 offset0:8 offset1:140
	v_lshlrev_b32_e32 v174, 1, v239
	v_and_b32_e32 v175, 8, v174
	v_and_b32_e32 v176, 0x7ffffff0, v239
	v_bitop3_b32 v175, v175, v74, v176 bitop3:0x36
	v_lshlrev_b32_e32 v175, 1, v175
	v_and_b32_e32 v174, 4, v174
	v_add3_u32 v174, s37, v175, v174
	v_and_b32_e32 v175, 8, v239
	s_waitcnt vmcnt(10)
	v_cvt_pk_bf16_f32 v176, v190, v194
	v_add3_u32 v174, v174, v175, v178
	v_cvt_pk_bf16_f32 v175, v191, v195
	ds_write2_b32 v174, v176, v175 offset1:132
	v_cvt_pk_bf16_f32 v175, v192, v196
	v_cvt_pk_bf16_f32 v176, v193, v197
	v_add_u32_e32 v174, 0x400, v174
	ds_write2_b32 v174, v175, v176 offset0:8 offset1:140
	v_lshlrev_b32_e32 v174, 1, v240
	v_and_b32_e32 v175, 8, v174
	v_and_b32_e32 v176, 0x7ffffff0, v240
	v_bitop3_b32 v175, v175, v74, v176 bitop3:0x36
	v_lshlrev_b32_e32 v175, 1, v175
	v_and_b32_e32 v174, 4, v174
	v_add3_u32 v174, s37, v175, v174
	v_and_b32_e32 v175, 8, v240
	s_waitcnt vmcnt(8)
	v_cvt_pk_bf16_f32 v176, v198, v202
	v_add3_u32 v174, v174, v175, v178
	v_cvt_pk_bf16_f32 v175, v199, v203
	ds_write2_b32 v174, v176, v175 offset1:132
	v_cvt_pk_bf16_f32 v175, v200, v204
	v_cvt_pk_bf16_f32 v176, v201, v205
	v_add_u32_e32 v174, 0x400, v174
	ds_write2_b32 v174, v175, v176 offset0:8 offset1:140
	v_lshlrev_b32_e32 v174, 1, v241
	v_and_b32_e32 v175, 8, v174
	v_and_b32_e32 v176, 0x7ffffff0, v241
	v_bitop3_b32 v175, v175, v74, v176 bitop3:0x36
	v_lshlrev_b32_e32 v175, 1, v175
	v_and_b32_e32 v174, 4, v174
	v_add3_u32 v174, s37, v175, v174
	v_and_b32_e32 v175, 8, v241
	s_waitcnt vmcnt(6)
	v_cvt_pk_bf16_f32 v176, v206, v210
	v_add3_u32 v174, v174, v175, v178
	v_cvt_pk_bf16_f32 v175, v207, v211
	ds_write2_b32 v174, v176, v175 offset1:132
	v_cvt_pk_bf16_f32 v175, v208, v212
	v_cvt_pk_bf16_f32 v176, v209, v213
	v_add_u32_e32 v174, 0x400, v174
	ds_write2_b32 v174, v175, v176 offset0:8 offset1:140
	v_lshlrev_b32_e32 v174, 1, v242
	v_and_b32_e32 v175, 8, v174
	v_and_b32_e32 v176, 0x7ffffff0, v242
	v_bitop3_b32 v175, v175, v74, v176 bitop3:0x36
	v_lshlrev_b32_e32 v175, 1, v175
	v_and_b32_e32 v174, 4, v174
	v_add3_u32 v174, s37, v175, v174
	v_and_b32_e32 v175, 8, v242
	s_waitcnt vmcnt(4)
	v_cvt_pk_bf16_f32 v176, v214, v218
	v_add3_u32 v174, v174, v175, v178
	v_cvt_pk_bf16_f32 v175, v215, v219
	ds_write2_b32 v174, v176, v175 offset1:132
	v_cvt_pk_bf16_f32 v175, v216, v220
	v_cvt_pk_bf16_f32 v176, v217, v221
	v_add_u32_e32 v174, 0x400, v174
	ds_write2_b32 v174, v175, v176 offset0:8 offset1:140
	v_lshlrev_b32_e32 v174, 1, v243
	v_and_b32_e32 v175, 8, v174
	v_and_b32_e32 v176, 0x7ffffff0, v243
	v_bitop3_b32 v175, v175, v74, v176 bitop3:0x36
	v_lshlrev_b32_e32 v175, 1, v175
	v_and_b32_e32 v174, 4, v174
	v_add3_u32 v174, s37, v175, v174
	v_and_b32_e32 v175, 8, v243
	s_waitcnt vmcnt(2)
	v_cvt_pk_bf16_f32 v176, v222, v226
	v_add3_u32 v174, v174, v175, v178
	v_cvt_pk_bf16_f32 v175, v223, v227
	ds_write2_b32 v174, v176, v175 offset1:132
	v_cvt_pk_bf16_f32 v175, v224, v228
	v_cvt_pk_bf16_f32 v176, v225, v229
	v_add_u32_e32 v174, 0x400, v174
	ds_write2_b32 v174, v175, v176 offset0:8 offset1:140
	v_lshlrev_b32_e32 v174, 1, v165
	v_and_b32_e32 v175, 8, v174
	v_and_b32_e32 v176, 0x7ffffff0, v165
	v_bitop3_b32 v175, v175, v74, v176 bitop3:0x36
	v_lshlrev_b32_e32 v175, 1, v175
	v_and_b32_e32 v174, 4, v174
	v_add3_u32 v174, s37, v175, v174
	v_and_b32_e32 v175, 8, v165
	s_waitcnt vmcnt(0)
	v_cvt_pk_bf16_f32 v176, v230, v234
	v_add3_u32 v174, v174, v175, v178
	v_cvt_pk_bf16_f32 v175, v231, v235
	ds_write2_b32 v174, v176, v175 offset1:132
	v_cvt_pk_bf16_f32 v175, v232, v236
	v_cvt_pk_bf16_f32 v176, v233, v237
	v_add_u32_e32 v174, 0x400, v174
	s_cmp_gt_u32 s13, 63
	v_mov_b32_e32 v74, 0
	v_readlane_b32 s21, v245, 11
	v_readlane_b32 s22, v245, 12
	v_readlane_b32 s23, v245, 13
	v_readlane_b32 s28, v245, 18
	v_readlane_b32 s29, v245, 19
	v_readlane_b32 s30, v245, 20
	v_readlane_b32 s31, v245, 21
	ds_write2_b32 v174, v175, v176 offset0:8 offset1:140
	s_waitcnt lgkmcnt(0)
	s_barrier
	s_cbranch_scc1 .LBB0_1239
	s_lshl_b64 s[6:7], s[0:1], 10
	s_add_u32 s6, s41, s6
	s_addc_u32 s7, s42, s7
	s_lshl_b32 s14, s12, 1
	s_add_u32 s6, s6, s14
	s_addc_u32 s7, s7, 0
	v_lshlrev_b32_e32 v158, 10, v163
	v_lshl_add_u64 v[2:3], s[6:7], 0, v[158:159]
	v_mov_b32_e32 v161, v159
	v_cmp_gt_u32_e32 vcc, 8, v163
	v_lshl_add_u64 v[2:3], v[2:3], 0, v[160:161]
	s_nop 0
	v_mov_b32_e32 v18, v166
	v_mov_b32_e32 v19, v167
	v_mov_b32_e32 v20, v168
	v_mov_b32_e32 v21, v169
	s_and_saveexec_b64 s[6:7], vcc
	s_cbranch_execz .LBB0_1224
	s_nop 0
.LBB0_1224:
	s_or_b64 exec, exec, s[6:7]
	s_nop 0
	s_nop 0
	s_nop 0
	s_and_saveexec_b64 s[6:7], vcc
	s_cbranch_execz .LBB0_1226
	s_nop 0
.LBB0_1226:
	s_or_b64 exec, exec, s[6:7]
	s_nop 0
	s_nop 0
	s_nop 0
	s_nop 0
	s_nop 0
	s_and_saveexec_b64 s[6:7], vcc
	s_cbranch_execz .LBB0_1228
	s_nop 0
